# phase 3 k_pe/gate tiles: hand-written epilogue, all cos/sin loads in flight, then rope math and stores
# speedup vs baseline: 1.0051x; 1.0051x over previous
.LBB0_1112:
	s_cmp_lt_i32 s40, 0
	s_cbranch_scc1 .LBB0_1111
	v_mov_b32_e32 v0, v161
	v_mov_b32_e32 v31, v186
	s_add_i32 s12, s41, 0xffffe000
	s_mov_b32 s13, s77
	s_lshl_b64 s[78:79], s[12:13], 11
	v_lshlrev_b32_e32 v1, 4, v31
	v_ashrrev_i32_e32 v32, 3, v31
	v_and_b32_e32 v30, 0x70, v1
	s_add_u32 vcc_lo, s39, s78
	v_readlane_b32 s13, v254, 36
	v_lshl_or_b32 v34, v32, 11, v30
	s_addc_u32 vcc_hi, s13, s79
	v_add_u32_e32 v35, 0x10000, v34
	v_add_u32_e32 v38, 0x20000, v34
	v_add_u32_e32 v39, 0x30000, v34
	s_barrier
	global_load_dwordx4 v[14:17], v34, vcc
	global_load_dwordx4 v[18:21], v35, vcc
	global_load_dwordx4 v[22:25], v38, vcc
	global_load_dwordx4 v[26:29], v39, vcc
	global_load_dwordx4 v[46:49], v34, s[10:11]
	global_load_dwordx4 v[50:53], v35, s[10:11]
	v_lshrrev_b32_e32 v33, 1, v31
	v_and_b32_e32 v31, 31, v31
	v_and_or_b32 v45, v33, 32, v31
	v_and_or_b32 v31, v33, s44, v31
	v_and_b32_e32 v78, 16, v33
	v_mad_u64_u32 v[32:33], s[78:79], v32, s43, v[30:31]
	v_mad_u64_u32 v[36:37], s[78:79], v31, s43, v[78:79]
	v_mad_u32_u24 v33, v45, s43, v78
	v_mov_b32_e32 v1, v0
	v_mov_b32_e32 v2, v0
	v_mov_b32_e32 v3, v0
	v_mov_b32_e32 v4, v0
	v_mov_b32_e32 v5, v0
	v_mov_b32_e32 v6, v0
	v_mov_b32_e32 v7, v0
	s_waitcnt vmcnt(6)
	v_mov_b32_e32 v8, v0
	v_mov_b32_e32 v9, v0
	v_mov_b32_e32 v10, v0
	v_mov_b32_e32 v11, v0
	v_mov_b32_e32 v12, v0
	v_mov_b32_e32 v13, v0
	s_waitcnt vmcnt(5)
	ds_write_b128 v32, v[14:17]
	s_waitcnt vmcnt(4)
	ds_write_b128 v32, v[18:21] offset:4608
	s_waitcnt vmcnt(3)
	ds_write_b128 v32, v[22:25] offset:9216
	s_waitcnt vmcnt(2)
	ds_write_b128 v32, v[26:29] offset:13824
	s_waitcnt vmcnt(1)
	ds_write_b128 v32, v[46:49] offset:36864
	s_waitcnt vmcnt(0)
	ds_write_b128 v32, v[50:53] offset:41472
	global_load_dwordx4 v[46:49], v34, vcc offset:128
	global_load_dwordx4 v[50:53], v35, vcc offset:128
	global_load_dwordx4 v[58:61], v38, vcc offset:128
	global_load_dwordx4 v[62:65], v39, vcc offset:128
	global_load_dwordx4 v[66:69], v34, s[18:19]
	global_load_dwordx4 v[70:73], v35, s[18:19]
	s_waitcnt lgkmcnt(0)
	s_barrier
	ds_read_b128 v[74:77], v36
	ds_read_b128 v[78:81], v36 offset:4608
	ds_read_b128 v[82:85], v36 offset:32
	ds_read_b128 v[86:89], v33 offset:36864
	v_mov_b32_e32 v14, v0
	v_mov_b32_e32 v15, v0
	ds_read_b128 v[90:93], v36 offset:4640
	ds_read_b128 v[94:97], v33 offset:36896
	s_waitcnt lgkmcnt(2)
	v_mfma_f32_32x32x16_bf16 v[16:31], v[74:77], v[86:89], v[0:15]
	v_mfma_f32_32x32x16_bf16 v[0:15], v[78:81], v[86:89], v[0:15]
	s_waitcnt lgkmcnt(0)
	v_mfma_f32_32x32x16_bf16 v[16:31], v[82:85], v[94:97], v[16:31]
	v_mfma_f32_32x32x16_bf16 v[0:15], v[90:93], v[94:97], v[0:15]
	ds_read_b128 v[74:77], v36 offset:64
	ds_read_b128 v[82:85], v36 offset:4672
	ds_read_b128 v[78:81], v33 offset:36928
	s_waitcnt lgkmcnt(0)
	v_mfma_f32_32x32x16_bf16 v[16:31], v[74:77], v[78:81], v[16:31]
	v_mfma_f32_32x32x16_bf16 v[0:15], v[82:85], v[78:81], v[0:15]
	global_load_dwordx4 v[74:77], v34, vcc offset:256
	global_load_dwordx4 v[78:81], v35, vcc offset:256
	global_load_dwordx4 v[82:85], v38, vcc offset:256
	global_load_dwordx4 v[86:89], v39, vcc offset:256
	global_load_dwordx4 v[90:93], v34, s[20:21]
	global_load_dwordx4 v[94:97], v35, s[20:21]
	s_waitcnt vmcnt(11)
	ds_write_b128 v32, v[46:49] offset:18432
	s_waitcnt vmcnt(10)
	ds_write_b128 v32, v[50:53] offset:23040
	s_waitcnt vmcnt(9)
	ds_write_b128 v32, v[58:61] offset:27648
	s_waitcnt vmcnt(8)
	ds_write_b128 v32, v[62:65] offset:32256
	ds_read_b128 v[46:49], v36 offset:96
	ds_read_b128 v[58:61], v36 offset:4704
	ds_read_b128 v[50:53], v33 offset:36960
	s_waitcnt vmcnt(7)
	ds_write_b128 v32, v[66:69] offset:46080
	s_waitcnt vmcnt(6)
	ds_write_b128 v32, v[70:73] offset:50688
	s_waitcnt lgkmcnt(2)
	v_mfma_f32_32x32x16_bf16 v[16:31], v[46:49], v[50:53], v[16:31]
	s_waitcnt lgkmcnt(0)
	s_barrier
	v_mfma_f32_32x32x16_bf16 v[0:15], v[58:61], v[50:53], v[0:15]
	ds_read_b128 v[46:49], v36 offset:18432
	ds_read_b128 v[58:61], v36 offset:23040
	ds_read_b128 v[50:53], v33 offset:46080
	ds_read_b128 v[62:65], v36 offset:18464
	ds_read_b128 v[66:69], v36 offset:23072
	ds_read_b128 v[70:73], v33 offset:46112
	s_waitcnt lgkmcnt(3)
	v_mfma_f32_32x32x16_bf16 v[16:31], v[46:49], v[50:53], v[16:31]
	v_mfma_f32_32x32x16_bf16 v[0:15], v[58:61], v[50:53], v[0:15]
	global_load_dwordx4 v[46:49], v34, vcc offset:384
	global_load_dwordx4 v[50:53], v35, vcc offset:384
	global_load_dwordx4 v[58:61], v38, vcc offset:384
	global_load_dwordx4 v[98:101], v39, vcc offset:384
	global_load_dwordx4 v[102:105], v34, s[22:23]
	global_load_dwordx4 v[106:109], v35, s[22:23]
	ds_read_b128 v[110:113], v36 offset:18496
	ds_read_b128 v[114:117], v36 offset:23104
	ds_read_b128 v[118:121], v33 offset:46144
	s_waitcnt vmcnt(11)
	ds_write_b128 v32, v[74:77]
	s_waitcnt vmcnt(10)
	ds_write_b128 v32, v[78:81] offset:4608
	s_waitcnt vmcnt(9)
	ds_write_b128 v32, v[82:85] offset:9216
	s_waitcnt vmcnt(8)
	ds_write_b128 v32, v[86:89] offset:13824
	s_waitcnt lgkmcnt(7)
	v_mfma_f32_32x32x16_bf16 v[16:31], v[62:65], v[70:73], v[16:31]
	v_mfma_f32_32x32x16_bf16 v[0:15], v[66:69], v[70:73], v[0:15]
	ds_read_b128 v[62:65], v36 offset:18528
	ds_read_b128 v[66:69], v36 offset:23136
	ds_read_b128 v[70:73], v33 offset:46176
	s_waitcnt vmcnt(7)
	ds_write_b128 v32, v[90:93] offset:36864
	s_waitcnt vmcnt(6)
	ds_write_b128 v32, v[94:97] offset:41472
	s_waitcnt lgkmcnt(0)
	s_barrier
	v_mfma_f32_32x32x16_bf16 v[16:31], v[110:113], v[118:121], v[16:31]
	v_mfma_f32_32x32x16_bf16 v[0:15], v[114:117], v[118:121], v[0:15]
	v_mfma_f32_32x32x16_bf16 v[16:31], v[62:65], v[70:73], v[16:31]
	v_mfma_f32_32x32x16_bf16 v[0:15], v[66:69], v[70:73], v[0:15]
	ds_read_b128 v[62:65], v36
	ds_read_b128 v[70:73], v36 offset:4608
	ds_read_b128 v[66:69], v33 offset:36864
	ds_read_b128 v[74:77], v36 offset:32
	ds_read_b128 v[78:81], v36 offset:4640
	ds_read_b128 v[82:85], v33 offset:36896
	s_waitcnt lgkmcnt(3)
	v_mfma_f32_32x32x16_bf16 v[16:31], v[62:65], v[66:69], v[16:31]
	v_mfma_f32_32x32x16_bf16 v[0:15], v[70:73], v[66:69], v[0:15]
	global_load_dwordx4 v[62:65], v34, vcc offset:512
	global_load_dwordx4 v[66:69], v35, vcc offset:512
	global_load_dwordx4 v[70:73], v38, vcc offset:512
	global_load_dwordx4 v[86:89], v39, vcc offset:512
	global_load_dwordx4 v[90:93], v34, s[24:25]
	global_load_dwordx4 v[94:97], v35, s[24:25]
	ds_read_b128 v[110:113], v36 offset:64
	ds_read_b128 v[114:117], v36 offset:4672
	ds_read_b128 v[118:121], v33 offset:36928
	s_waitcnt vmcnt(11)
	ds_write_b128 v32, v[46:49] offset:18432
	s_waitcnt vmcnt(10)
	ds_write_b128 v32, v[50:53] offset:23040
	s_waitcnt vmcnt(9)
	ds_write_b128 v32, v[58:61] offset:27648
	s_waitcnt vmcnt(8)
	ds_write_b128 v32, v[98:101] offset:32256
	s_waitcnt lgkmcnt(7)
	v_mfma_f32_32x32x16_bf16 v[16:31], v[74:77], v[82:85], v[16:31]
	v_mfma_f32_32x32x16_bf16 v[0:15], v[78:81], v[82:85], v[0:15]
	ds_read_b128 v[46:49], v36 offset:96
	ds_read_b128 v[50:53], v36 offset:4704
	ds_read_b128 v[58:61], v33 offset:36960
	s_waitcnt vmcnt(7)
	ds_write_b128 v32, v[102:105] offset:46080
	s_waitcnt vmcnt(6)
	ds_write_b128 v32, v[106:109] offset:50688
	s_waitcnt lgkmcnt(0)
	s_barrier
	v_mfma_f32_32x32x16_bf16 v[16:31], v[110:113], v[118:121], v[16:31]
	v_mfma_f32_32x32x16_bf16 v[0:15], v[114:117], v[118:121], v[0:15]
	v_mfma_f32_32x32x16_bf16 v[16:31], v[46:49], v[58:61], v[16:31]
	v_mfma_f32_32x32x16_bf16 v[0:15], v[50:53], v[58:61], v[0:15]
	ds_read_b128 v[46:49], v36 offset:18432
	ds_read_b128 v[58:61], v36 offset:23040
	ds_read_b128 v[50:53], v33 offset:46080
	ds_read_b128 v[74:77], v36 offset:18464
	ds_read_b128 v[78:81], v36 offset:23072
	ds_read_b128 v[82:85], v33 offset:46112
	s_waitcnt lgkmcnt(3)
	v_mfma_f32_32x32x16_bf16 v[16:31], v[46:49], v[50:53], v[16:31]
	v_mfma_f32_32x32x16_bf16 v[0:15], v[58:61], v[50:53], v[0:15]
	global_load_dwordx4 v[46:49], v34, vcc offset:640
	global_load_dwordx4 v[50:53], v35, vcc offset:640
	global_load_dwordx4 v[58:61], v38, vcc offset:640
	global_load_dwordx4 v[98:101], v39, vcc offset:640
	global_load_dwordx4 v[102:105], v34, s[26:27]
	global_load_dwordx4 v[106:109], v35, s[26:27]
	ds_read_b128 v[110:113], v36 offset:18496
	ds_read_b128 v[114:117], v36 offset:23104
	ds_read_b128 v[118:121], v33 offset:46144
	s_waitcnt vmcnt(11)
	ds_write_b128 v32, v[62:65]
	s_waitcnt vmcnt(10)
	ds_write_b128 v32, v[66:69] offset:4608
	s_waitcnt vmcnt(9)
	ds_write_b128 v32, v[70:73] offset:9216
	s_waitcnt vmcnt(8)
	ds_write_b128 v32, v[86:89] offset:13824
	s_waitcnt lgkmcnt(7)
	v_mfma_f32_32x32x16_bf16 v[16:31], v[74:77], v[82:85], v[16:31]
	v_mfma_f32_32x32x16_bf16 v[0:15], v[78:81], v[82:85], v[0:15]
	ds_read_b128 v[62:65], v36 offset:18528
	ds_read_b128 v[66:69], v36 offset:23136
	ds_read_b128 v[70:73], v33 offset:46176
	s_waitcnt vmcnt(7)
	ds_write_b128 v32, v[90:93] offset:36864
	s_waitcnt vmcnt(6)
	ds_write_b128 v32, v[94:97] offset:41472
	s_waitcnt lgkmcnt(0)
	s_barrier
	v_mfma_f32_32x32x16_bf16 v[16:31], v[110:113], v[118:121], v[16:31]
	v_mfma_f32_32x32x16_bf16 v[0:15], v[114:117], v[118:121], v[0:15]
	v_mfma_f32_32x32x16_bf16 v[16:31], v[62:65], v[70:73], v[16:31]
	v_mfma_f32_32x32x16_bf16 v[0:15], v[66:69], v[70:73], v[0:15]
	ds_read_b128 v[62:65], v36
	ds_read_b128 v[70:73], v36 offset:4608
	ds_read_b128 v[66:69], v33 offset:36864
	ds_read_b128 v[74:77], v36 offset:32
	ds_read_b128 v[78:81], v36 offset:4640
	ds_read_b128 v[82:85], v33 offset:36896
	s_waitcnt lgkmcnt(3)
	v_mfma_f32_32x32x16_bf16 v[16:31], v[62:65], v[66:69], v[16:31]
	v_mfma_f32_32x32x16_bf16 v[0:15], v[70:73], v[66:69], v[0:15]
	global_load_dwordx4 v[62:65], v34, vcc offset:768
	global_load_dwordx4 v[66:69], v35, vcc offset:768
	global_load_dwordx4 v[70:73], v38, vcc offset:768
	global_load_dwordx4 v[86:89], v39, vcc offset:768
	global_load_dwordx4 v[90:93], v34, s[28:29]
	global_load_dwordx4 v[94:97], v35, s[28:29]
	ds_read_b128 v[110:113], v36 offset:64
	ds_read_b128 v[114:117], v36 offset:4672
	ds_read_b128 v[118:121], v33 offset:36928
	s_waitcnt vmcnt(11)
	ds_write_b128 v32, v[46:49] offset:18432
	s_waitcnt vmcnt(10)
	ds_write_b128 v32, v[50:53] offset:23040
	s_waitcnt vmcnt(9)
	ds_write_b128 v32, v[58:61] offset:27648
	s_waitcnt vmcnt(8)
	ds_write_b128 v32, v[98:101] offset:32256
	s_waitcnt lgkmcnt(7)
	v_mfma_f32_32x32x16_bf16 v[16:31], v[74:77], v[82:85], v[16:31]
	v_mfma_f32_32x32x16_bf16 v[0:15], v[78:81], v[82:85], v[0:15]
	ds_read_b128 v[46:49], v36 offset:96
	ds_read_b128 v[50:53], v36 offset:4704
	ds_read_b128 v[58:61], v33 offset:36960
	s_waitcnt vmcnt(7)
	ds_write_b128 v32, v[102:105] offset:46080
	s_waitcnt vmcnt(6)
	ds_write_b128 v32, v[106:109] offset:50688
	s_waitcnt lgkmcnt(0)
	s_barrier
	v_mfma_f32_32x32x16_bf16 v[16:31], v[110:113], v[118:121], v[16:31]
	v_mfma_f32_32x32x16_bf16 v[0:15], v[114:117], v[118:121], v[0:15]
	v_mfma_f32_32x32x16_bf16 v[16:31], v[46:49], v[58:61], v[16:31]
	v_mfma_f32_32x32x16_bf16 v[0:15], v[50:53], v[58:61], v[0:15]
	ds_read_b128 v[46:49], v36 offset:18432
	ds_read_b128 v[58:61], v36 offset:23040
	ds_read_b128 v[50:53], v33 offset:46080
	ds_read_b128 v[74:77], v36 offset:18464
	ds_read_b128 v[78:81], v36 offset:23072
	ds_read_b128 v[82:85], v33 offset:46112
	s_waitcnt lgkmcnt(3)
	v_mfma_f32_32x32x16_bf16 v[16:31], v[46:49], v[50:53], v[16:31]
	v_mfma_f32_32x32x16_bf16 v[0:15], v[58:61], v[50:53], v[0:15]
	global_load_dwordx4 v[46:49], v34, vcc offset:896
	global_load_dwordx4 v[50:53], v35, vcc offset:896
	global_load_dwordx4 v[58:61], v38, vcc offset:896
	global_load_dwordx4 v[98:101], v39, vcc offset:896
	global_load_dwordx4 v[102:105], v34, s[30:31]
	global_load_dwordx4 v[106:109], v35, s[30:31]
	ds_read_b128 v[110:113], v36 offset:18496
	ds_read_b128 v[114:117], v36 offset:23104
	ds_read_b128 v[118:121], v33 offset:46144
	s_waitcnt vmcnt(11)
	ds_write_b128 v32, v[62:65]
	s_waitcnt vmcnt(10)
	ds_write_b128 v32, v[66:69] offset:4608
	s_waitcnt vmcnt(9)
	ds_write_b128 v32, v[70:73] offset:9216
	s_waitcnt vmcnt(8)
	ds_write_b128 v32, v[86:89] offset:13824
	s_waitcnt lgkmcnt(7)
	v_mfma_f32_32x32x16_bf16 v[16:31], v[74:77], v[82:85], v[16:31]
	v_mfma_f32_32x32x16_bf16 v[0:15], v[78:81], v[82:85], v[0:15]
	ds_read_b128 v[62:65], v36 offset:18528
	ds_read_b128 v[66:69], v36 offset:23136
	ds_read_b128 v[70:73], v33 offset:46176
	s_waitcnt vmcnt(7)
	ds_write_b128 v32, v[90:93] offset:36864
	s_waitcnt vmcnt(6)
	ds_write_b128 v32, v[94:97] offset:41472
	s_waitcnt lgkmcnt(0)
	s_barrier
	v_mfma_f32_32x32x16_bf16 v[16:31], v[110:113], v[118:121], v[16:31]
	v_mfma_f32_32x32x16_bf16 v[0:15], v[114:117], v[118:121], v[0:15]
	v_mfma_f32_32x32x16_bf16 v[16:31], v[62:65], v[70:73], v[16:31]
	v_mfma_f32_32x32x16_bf16 v[0:15], v[66:69], v[70:73], v[0:15]
	ds_read_b128 v[62:65], v36
	ds_read_b128 v[70:73], v36 offset:4608
	ds_read_b128 v[66:69], v33 offset:36864
	ds_read_b128 v[74:77], v36 offset:32
	ds_read_b128 v[78:81], v36 offset:4640
	ds_read_b128 v[82:85], v33 offset:36896
	s_waitcnt lgkmcnt(3)
	v_mfma_f32_32x32x16_bf16 v[16:31], v[62:65], v[66:69], v[16:31]
	v_mfma_f32_32x32x16_bf16 v[0:15], v[70:73], v[66:69], v[0:15]
	global_load_dwordx4 v[62:65], v34, vcc offset:1024
	global_load_dwordx4 v[66:69], v35, vcc offset:1024
	global_load_dwordx4 v[70:73], v38, vcc offset:1024
	global_load_dwordx4 v[86:89], v39, vcc offset:1024
	global_load_dwordx4 v[90:93], v34, s[34:35]
	global_load_dwordx4 v[94:97], v35, s[34:35]
	ds_read_b128 v[110:113], v36 offset:64
	ds_read_b128 v[114:117], v36 offset:4672
	ds_read_b128 v[118:121], v33 offset:36928
	s_waitcnt vmcnt(11)
	ds_write_b128 v32, v[46:49] offset:18432
	s_waitcnt vmcnt(10)
	ds_write_b128 v32, v[50:53] offset:23040
	s_waitcnt vmcnt(9)
	ds_write_b128 v32, v[58:61] offset:27648
	s_waitcnt vmcnt(8)
	ds_write_b128 v32, v[98:101] offset:32256
	s_waitcnt lgkmcnt(7)
	v_mfma_f32_32x32x16_bf16 v[16:31], v[74:77], v[82:85], v[16:31]
	v_mfma_f32_32x32x16_bf16 v[0:15], v[78:81], v[82:85], v[0:15]
	ds_read_b128 v[46:49], v36 offset:96
	ds_read_b128 v[50:53], v36 offset:4704
	ds_read_b128 v[58:61], v33 offset:36960
	s_waitcnt vmcnt(7)
	ds_write_b128 v32, v[102:105] offset:46080
	s_waitcnt vmcnt(6)
	ds_write_b128 v32, v[106:109] offset:50688
	s_waitcnt lgkmcnt(0)
	s_barrier
	v_mfma_f32_32x32x16_bf16 v[16:31], v[110:113], v[118:121], v[16:31]
	v_mfma_f32_32x32x16_bf16 v[0:15], v[114:117], v[118:121], v[0:15]
	v_mfma_f32_32x32x16_bf16 v[16:31], v[46:49], v[58:61], v[16:31]
	v_mfma_f32_32x32x16_bf16 v[0:15], v[50:53], v[58:61], v[0:15]
	ds_read_b128 v[46:49], v36 offset:18432
	ds_read_b128 v[58:61], v36 offset:23040
	ds_read_b128 v[50:53], v33 offset:46080
	ds_read_b128 v[74:77], v36 offset:18464
	ds_read_b128 v[78:81], v36 offset:23072
	ds_read_b128 v[82:85], v33 offset:46112
	s_waitcnt lgkmcnt(3)
	v_mfma_f32_32x32x16_bf16 v[16:31], v[46:49], v[50:53], v[16:31]
	v_mfma_f32_32x32x16_bf16 v[0:15], v[58:61], v[50:53], v[0:15]
	global_load_dwordx4 v[46:49], v34, vcc offset:1152
	global_load_dwordx4 v[50:53], v35, vcc offset:1152
	global_load_dwordx4 v[58:61], v38, vcc offset:1152
	global_load_dwordx4 v[98:101], v39, vcc offset:1152
	global_load_dwordx4 v[102:105], v34, s[14:15]
	global_load_dwordx4 v[106:109], v35, s[14:15]
	ds_read_b128 v[110:113], v36 offset:18496
	ds_read_b128 v[114:117], v36 offset:23104
	ds_read_b128 v[118:121], v33 offset:46144
	s_waitcnt vmcnt(11)
	ds_write_b128 v32, v[62:65]
	s_waitcnt vmcnt(10)
	ds_write_b128 v32, v[66:69] offset:4608
	s_waitcnt vmcnt(9)
	ds_write_b128 v32, v[70:73] offset:9216
	s_waitcnt vmcnt(8)
	ds_write_b128 v32, v[86:89] offset:13824
	s_waitcnt lgkmcnt(7)
	v_mfma_f32_32x32x16_bf16 v[16:31], v[74:77], v[82:85], v[16:31]
	v_mfma_f32_32x32x16_bf16 v[0:15], v[78:81], v[82:85], v[0:15]
	ds_read_b128 v[62:65], v36 offset:18528
	ds_read_b128 v[66:69], v36 offset:23136
	ds_read_b128 v[70:73], v33 offset:46176
	s_waitcnt vmcnt(7)
	ds_write_b128 v32, v[90:93] offset:36864
	s_waitcnt vmcnt(6)
	ds_write_b128 v32, v[94:97] offset:41472
	s_waitcnt lgkmcnt(0)
	s_barrier
	v_mfma_f32_32x32x16_bf16 v[16:31], v[110:113], v[118:121], v[16:31]
	v_mfma_f32_32x32x16_bf16 v[0:15], v[114:117], v[118:121], v[0:15]
	v_mfma_f32_32x32x16_bf16 v[16:31], v[62:65], v[70:73], v[16:31]
	v_mfma_f32_32x32x16_bf16 v[0:15], v[66:69], v[70:73], v[0:15]
	ds_read_b128 v[62:65], v36
	ds_read_b128 v[70:73], v36 offset:4608
	ds_read_b128 v[66:69], v33 offset:36864
	ds_read_b128 v[74:77], v36 offset:32
	ds_read_b128 v[78:81], v36 offset:4640
	ds_read_b128 v[82:85], v33 offset:36896
	s_waitcnt lgkmcnt(3)
	v_mfma_f32_32x32x16_bf16 v[16:31], v[62:65], v[66:69], v[16:31]
	v_mfma_f32_32x32x16_bf16 v[0:15], v[70:73], v[66:69], v[0:15]
	global_load_dwordx4 v[62:65], v34, vcc offset:1280
	global_load_dwordx4 v[66:69], v35, vcc offset:1280
	global_load_dwordx4 v[70:73], v38, vcc offset:1280
	global_load_dwordx4 v[86:89], v39, vcc offset:1280
	global_load_dwordx4 v[90:93], v34, s[52:53]
	global_load_dwordx4 v[94:97], v35, s[52:53]
	ds_read_b128 v[110:113], v36 offset:64
	ds_read_b128 v[114:117], v36 offset:4672
	ds_read_b128 v[118:121], v33 offset:36928
	s_waitcnt vmcnt(11)
	ds_write_b128 v32, v[46:49] offset:18432
	s_waitcnt vmcnt(10)
	ds_write_b128 v32, v[50:53] offset:23040
	s_waitcnt vmcnt(9)
	ds_write_b128 v32, v[58:61] offset:27648
	s_waitcnt vmcnt(8)
	ds_write_b128 v32, v[98:101] offset:32256
	s_waitcnt lgkmcnt(7)
	v_mfma_f32_32x32x16_bf16 v[16:31], v[74:77], v[82:85], v[16:31]
	v_mfma_f32_32x32x16_bf16 v[0:15], v[78:81], v[82:85], v[0:15]
	ds_read_b128 v[46:49], v36 offset:96
	ds_read_b128 v[50:53], v36 offset:4704
	ds_read_b128 v[58:61], v33 offset:36960
	s_waitcnt vmcnt(7)
	ds_write_b128 v32, v[102:105] offset:46080
	s_waitcnt vmcnt(6)
	ds_write_b128 v32, v[106:109] offset:50688
	s_waitcnt lgkmcnt(0)
	s_barrier
	v_mfma_f32_32x32x16_bf16 v[16:31], v[110:113], v[118:121], v[16:31]
	v_mfma_f32_32x32x16_bf16 v[0:15], v[114:117], v[118:121], v[0:15]
	v_mfma_f32_32x32x16_bf16 v[16:31], v[46:49], v[58:61], v[16:31]
	v_mfma_f32_32x32x16_bf16 v[0:15], v[50:53], v[58:61], v[0:15]
	ds_read_b128 v[46:49], v36 offset:18432
	ds_read_b128 v[58:61], v36 offset:23040
	ds_read_b128 v[50:53], v33 offset:46080
	ds_read_b128 v[74:77], v36 offset:18464
	ds_read_b128 v[78:81], v36 offset:23072
	ds_read_b128 v[82:85], v33 offset:46112
	s_waitcnt lgkmcnt(3)
	v_mfma_f32_32x32x16_bf16 v[16:31], v[46:49], v[50:53], v[16:31]
	v_mfma_f32_32x32x16_bf16 v[0:15], v[58:61], v[50:53], v[0:15]
	global_load_dwordx4 v[46:49], v34, vcc offset:1408
	global_load_dwordx4 v[50:53], v35, vcc offset:1408
	global_load_dwordx4 v[58:61], v38, vcc offset:1408
	global_load_dwordx4 v[98:101], v39, vcc offset:1408
	global_load_dwordx4 v[102:105], v34, s[96:97]
	global_load_dwordx4 v[106:109], v35, s[96:97]
	ds_read_b128 v[110:113], v36 offset:18496
	ds_read_b128 v[114:117], v36 offset:23104
	ds_read_b128 v[118:121], v33 offset:46144
	s_waitcnt vmcnt(11)
	ds_write_b128 v32, v[62:65]
	s_waitcnt vmcnt(10)
	ds_write_b128 v32, v[66:69] offset:4608
	s_waitcnt vmcnt(9)
	ds_write_b128 v32, v[70:73] offset:9216
	s_waitcnt vmcnt(8)
	ds_write_b128 v32, v[86:89] offset:13824
	s_waitcnt lgkmcnt(7)
	v_mfma_f32_32x32x16_bf16 v[16:31], v[74:77], v[82:85], v[16:31]
	v_mfma_f32_32x32x16_bf16 v[0:15], v[78:81], v[82:85], v[0:15]
	ds_read_b128 v[62:65], v36 offset:18528
	ds_read_b128 v[66:69], v36 offset:23136
	ds_read_b128 v[70:73], v33 offset:46176
	s_waitcnt vmcnt(7)
	ds_write_b128 v32, v[90:93] offset:36864
	s_waitcnt vmcnt(6)
	ds_write_b128 v32, v[94:97] offset:41472
	s_waitcnt lgkmcnt(0)
	s_barrier
	v_mfma_f32_32x32x16_bf16 v[16:31], v[110:113], v[118:121], v[16:31]
	v_mfma_f32_32x32x16_bf16 v[0:15], v[114:117], v[118:121], v[0:15]
	v_mfma_f32_32x32x16_bf16 v[16:31], v[62:65], v[70:73], v[16:31]
	v_mfma_f32_32x32x16_bf16 v[0:15], v[66:69], v[70:73], v[0:15]
	ds_read_b128 v[62:65], v36
	ds_read_b128 v[70:73], v36 offset:4608
	ds_read_b128 v[66:69], v33 offset:36864
	ds_read_b128 v[74:77], v36 offset:32
	ds_read_b128 v[78:81], v36 offset:4640
	ds_read_b128 v[82:85], v33 offset:36896
	s_waitcnt lgkmcnt(3)
	v_mfma_f32_32x32x16_bf16 v[16:31], v[62:65], v[66:69], v[16:31]
	v_mfma_f32_32x32x16_bf16 v[0:15], v[70:73], v[66:69], v[0:15]
	global_load_dwordx4 v[62:65], v34, vcc offset:1536
	global_load_dwordx4 v[66:69], v35, vcc offset:1536
	global_load_dwordx4 v[70:73], v38, vcc offset:1536
	global_load_dwordx4 v[86:89], v39, vcc offset:1536
	global_load_dwordx4 v[90:93], v34, s[68:69]
	global_load_dwordx4 v[94:97], v35, s[68:69]
	ds_read_b128 v[110:113], v36 offset:64
	ds_read_b128 v[114:117], v36 offset:4672
	ds_read_b128 v[118:121], v33 offset:36928
	s_waitcnt vmcnt(11)
	ds_write_b128 v32, v[46:49] offset:18432
	s_waitcnt vmcnt(10)
	ds_write_b128 v32, v[50:53] offset:23040
	s_waitcnt vmcnt(9)
	ds_write_b128 v32, v[58:61] offset:27648
	s_waitcnt vmcnt(8)
	ds_write_b128 v32, v[98:101] offset:32256
	s_waitcnt lgkmcnt(7)
	v_mfma_f32_32x32x16_bf16 v[16:31], v[74:77], v[82:85], v[16:31]
	v_mfma_f32_32x32x16_bf16 v[0:15], v[78:81], v[82:85], v[0:15]
	ds_read_b128 v[46:49], v36 offset:96
	ds_read_b128 v[50:53], v36 offset:4704
	ds_read_b128 v[58:61], v33 offset:36960
	s_waitcnt vmcnt(7)
	ds_write_b128 v32, v[102:105] offset:46080
	s_waitcnt vmcnt(6)
	ds_write_b128 v32, v[106:109] offset:50688
	s_waitcnt lgkmcnt(0)
	s_barrier
	v_mfma_f32_32x32x16_bf16 v[16:31], v[110:113], v[118:121], v[16:31]
	v_mfma_f32_32x32x16_bf16 v[0:15], v[114:117], v[118:121], v[0:15]
	v_mfma_f32_32x32x16_bf16 v[16:31], v[46:49], v[58:61], v[16:31]
	v_mfma_f32_32x32x16_bf16 v[0:15], v[50:53], v[58:61], v[0:15]
	ds_read_b128 v[46:49], v36 offset:18432
	ds_read_b128 v[58:61], v36 offset:23040
	ds_read_b128 v[50:53], v33 offset:46080
	ds_read_b128 v[74:77], v36 offset:18464
	ds_read_b128 v[78:81], v36 offset:23072
	ds_read_b128 v[82:85], v33 offset:46112
	s_waitcnt lgkmcnt(3)
	v_mfma_f32_32x32x16_bf16 v[16:31], v[46:49], v[50:53], v[16:31]
	v_mfma_f32_32x32x16_bf16 v[0:15], v[58:61], v[50:53], v[0:15]
	global_load_dwordx4 v[46:49], v34, vcc offset:1664
	global_load_dwordx4 v[50:53], v35, vcc offset:1664
	global_load_dwordx4 v[58:61], v38, vcc offset:1664
	global_load_dwordx4 v[98:101], v39, vcc offset:1664
	global_load_dwordx4 v[102:105], v34, s[70:71]
	global_load_dwordx4 v[106:109], v35, s[70:71]
	ds_read_b128 v[110:113], v36 offset:18496
	ds_read_b128 v[114:117], v36 offset:23104
	ds_read_b128 v[118:121], v33 offset:46144
	s_waitcnt vmcnt(11)
	ds_write_b128 v32, v[62:65]
	s_waitcnt vmcnt(10)
	ds_write_b128 v32, v[66:69] offset:4608
	s_waitcnt vmcnt(9)
	ds_write_b128 v32, v[70:73] offset:9216
	s_waitcnt vmcnt(8)
	ds_write_b128 v32, v[86:89] offset:13824
	s_waitcnt lgkmcnt(7)
	v_mfma_f32_32x32x16_bf16 v[16:31], v[74:77], v[82:85], v[16:31]
	v_mfma_f32_32x32x16_bf16 v[0:15], v[78:81], v[82:85], v[0:15]
	ds_read_b128 v[62:65], v36 offset:18528
	ds_read_b128 v[66:69], v36 offset:23136
	ds_read_b128 v[70:73], v33 offset:46176
	s_waitcnt vmcnt(7)
	ds_write_b128 v32, v[90:93] offset:36864
	s_waitcnt vmcnt(6)
	ds_write_b128 v32, v[94:97] offset:41472
	s_waitcnt lgkmcnt(0)
	s_barrier
	v_mfma_f32_32x32x16_bf16 v[16:31], v[110:113], v[118:121], v[16:31]
	v_mfma_f32_32x32x16_bf16 v[0:15], v[114:117], v[118:121], v[0:15]
	v_mfma_f32_32x32x16_bf16 v[16:31], v[62:65], v[70:73], v[16:31]
	v_mfma_f32_32x32x16_bf16 v[0:15], v[66:69], v[70:73], v[0:15]
	ds_read_b128 v[62:65], v36
	ds_read_b128 v[70:73], v36 offset:4608
	ds_read_b128 v[66:69], v33 offset:36864
	ds_read_b128 v[74:77], v36 offset:32
	ds_read_b128 v[78:81], v36 offset:4640
	ds_read_b128 v[82:85], v33 offset:36896
	s_waitcnt lgkmcnt(3)
	v_mfma_f32_32x32x16_bf16 v[16:31], v[62:65], v[66:69], v[16:31]
	v_mfma_f32_32x32x16_bf16 v[0:15], v[70:73], v[66:69], v[0:15]
	global_load_dwordx4 v[62:65], v34, vcc offset:1792
	global_load_dwordx4 v[66:69], v35, vcc offset:1792
	global_load_dwordx4 v[70:73], v38, vcc offset:1792
	global_load_dwordx4 v[86:89], v39, vcc offset:1792
	global_load_dwordx4 v[90:93], v34, s[72:73]
	global_load_dwordx4 v[94:97], v35, s[72:73]
	ds_read_b128 v[110:113], v36 offset:64
	ds_read_b128 v[114:117], v36 offset:4672
	ds_read_b128 v[118:121], v33 offset:36928
	s_waitcnt vmcnt(11)
	ds_write_b128 v32, v[46:49] offset:18432
	s_waitcnt vmcnt(10)
	ds_write_b128 v32, v[50:53] offset:23040
	s_waitcnt vmcnt(9)
	ds_write_b128 v32, v[58:61] offset:27648
	s_waitcnt vmcnt(8)
	ds_write_b128 v32, v[98:101] offset:32256
	s_waitcnt lgkmcnt(7)
	v_mfma_f32_32x32x16_bf16 v[16:31], v[74:77], v[82:85], v[16:31]
	v_mfma_f32_32x32x16_bf16 v[0:15], v[78:81], v[82:85], v[0:15]
	ds_read_b128 v[46:49], v36 offset:96
	ds_read_b128 v[50:53], v36 offset:4704
	ds_read_b128 v[58:61], v33 offset:36960
	s_waitcnt vmcnt(7)
	ds_write_b128 v32, v[102:105] offset:46080
	s_waitcnt vmcnt(6)
	ds_write_b128 v32, v[106:109] offset:50688
	s_waitcnt lgkmcnt(0)
	s_barrier
	v_mfma_f32_32x32x16_bf16 v[16:31], v[110:113], v[118:121], v[16:31]
	v_mfma_f32_32x32x16_bf16 v[0:15], v[114:117], v[118:121], v[0:15]
	v_mfma_f32_32x32x16_bf16 v[16:31], v[46:49], v[58:61], v[16:31]
	v_mfma_f32_32x32x16_bf16 v[0:15], v[50:53], v[58:61], v[0:15]
	ds_read_b128 v[58:61], v36 offset:23040
	ds_read_b128 v[50:53], v33 offset:46080
	ds_read_b128 v[46:49], v36 offset:18432
	ds_read_b128 v[78:81], v36 offset:23072
	ds_read_b128 v[74:77], v36 offset:18464
	ds_read_b128 v[82:85], v33 offset:46112
	s_waitcnt lgkmcnt(4)
	v_mfma_f32_32x32x16_bf16 v[0:15], v[58:61], v[50:53], v[0:15]
	s_waitcnt lgkmcnt(3)
	v_mfma_f32_32x32x16_bf16 v[16:31], v[46:49], v[50:53], v[16:31]
	global_load_dwordx4 v[46:49], v34, vcc offset:1920
	global_load_dwordx4 v[50:53], v35, vcc offset:1920
	global_load_dwordx4 v[58:61], v38, vcc offset:1920
	global_load_dwordx4 v[98:101], v39, vcc offset:1920
	global_load_dwordx4 v[102:105], v34, s[74:75]
	global_load_dwordx4 v[106:109], v35, s[74:75]
	ds_read_b128 v[114:117], v36 offset:23104
	ds_read_b128 v[110:113], v36 offset:18496
	ds_read_b128 v[118:121], v33 offset:46144
	s_waitcnt vmcnt(11)
	ds_write_b128 v32, v[62:65]
	s_waitcnt vmcnt(10)
	ds_write_b128 v32, v[66:69] offset:4608
	s_waitcnt vmcnt(9)
	ds_write_b128 v32, v[70:73] offset:9216
	s_waitcnt vmcnt(8)
	ds_write_b128 v32, v[86:89] offset:13824
	s_waitcnt lgkmcnt(7)
	v_mfma_f32_32x32x16_bf16 v[0:15], v[78:81], v[82:85], v[0:15]
	ds_read_b128 v[66:69], v36 offset:23136
	ds_read_b128 v[62:65], v36 offset:18528
	ds_read_b128 v[70:73], v33 offset:46176
	s_waitcnt vmcnt(7)
	ds_write_b128 v32, v[90:93] offset:36864
	s_waitcnt vmcnt(6)
	ds_write_b128 v32, v[94:97] offset:41472
	s_waitcnt lgkmcnt(0)
	s_barrier
	v_mfma_f32_32x32x16_bf16 v[0:15], v[114:117], v[118:121], v[0:15]
	v_mfma_f32_32x32x16_bf16 v[0:15], v[66:69], v[70:73], v[0:15]
	ds_read_b128 v[66:69], v33 offset:36864
	v_mfma_f32_32x32x16_bf16 v[16:31], v[74:77], v[82:85], v[16:31]
	v_mfma_f32_32x32x16_bf16 v[16:31], v[110:113], v[118:121], v[16:31]
	v_mfma_f32_32x32x16_bf16 v[16:31], v[62:65], v[70:73], v[16:31]
	ds_read_b128 v[62:65], v36
	s_waitcnt lgkmcnt(0)
	v_mfma_f32_32x32x16_bf16 v[16:31], v[62:65], v[66:69], v[16:31]
	ds_read_b128 v[62:65], v36 offset:4608
	s_waitcnt lgkmcnt(0)
	v_mfma_f32_32x32x16_bf16 v[0:15], v[62:65], v[66:69], v[0:15]
	ds_read_b128 v[62:65], v36 offset:32
	ds_read_b128 v[66:69], v33 offset:36896
	s_waitcnt lgkmcnt(0)
	v_mfma_f32_32x32x16_bf16 v[16:31], v[62:65], v[66:69], v[16:31]
	ds_read_b128 v[62:65], v36 offset:4640
	s_waitcnt lgkmcnt(0)
	v_mfma_f32_32x32x16_bf16 v[0:15], v[62:65], v[66:69], v[0:15]
	ds_read_b128 v[62:65], v36 offset:64
	ds_read_b128 v[66:69], v33 offset:36928
	s_waitcnt lgkmcnt(0)
	v_mfma_f32_32x32x16_bf16 v[16:31], v[62:65], v[66:69], v[16:31]
	ds_read_b128 v[62:65], v36 offset:4672
	s_waitcnt vmcnt(3)
	ds_write_b128 v32, v[58:61] offset:27648
	s_waitcnt vmcnt(2)
	ds_write_b128 v32, v[98:101] offset:32256
	ds_write_b128 v32, v[46:49] offset:18432
	ds_write_b128 v32, v[50:53] offset:23040
	ds_read_b128 v[46:49], v36 offset:96
	ds_read_b128 v[50:53], v33 offset:36960
	s_waitcnt lgkmcnt(0)
	v_mfma_f32_32x32x16_bf16 v[16:31], v[46:49], v[50:53], v[16:31]
	ds_read_b128 v[46:49], v36 offset:4704
	v_add_u32_e32 v58, s41, v57
	v_add_u32_e32 v45, 0xffffe000, v58
	v_mfma_f32_32x32x16_bf16 v[0:15], v[62:65], v[66:69], v[0:15]
	s_waitcnt lgkmcnt(0)
	v_mfma_f32_32x32x16_bf16 v[0:15], v[46:49], v[50:53], v[0:15]
	s_waitcnt vmcnt(1)
	ds_write_b128 v32, v[102:105] offset:46080
	s_waitcnt vmcnt(0)
	ds_write_b128 v32, v[106:109] offset:50688
	s_waitcnt lgkmcnt(0)
	s_barrier
	ds_read_b128 v[46:49], v36 offset:18432
	ds_read_b128 v[50:53], v33 offset:46080
	s_waitcnt lgkmcnt(0)
	v_mfma_f32_32x32x16_bf16 v[16:31], v[46:49], v[50:53], v[16:31]
	ds_read_b128 v[46:49], v36 offset:23040
	s_waitcnt lgkmcnt(0)
	v_mfma_f32_32x32x16_bf16 v[0:15], v[46:49], v[50:53], v[0:15]
	ds_read_b128 v[46:49], v36 offset:18464
	ds_read_b128 v[50:53], v33 offset:46112
	s_waitcnt lgkmcnt(0)
	v_mfma_f32_32x32x16_bf16 v[16:31], v[46:49], v[50:53], v[16:31]
	ds_read_b128 v[46:49], v36 offset:23072
	s_waitcnt lgkmcnt(0)
	v_mfma_f32_32x32x16_bf16 v[0:15], v[46:49], v[50:53], v[0:15]
	ds_read_b128 v[46:49], v36 offset:18496
	ds_read_b128 v[50:53], v33 offset:46144
	ds_read_b128 v[32:35], v33 offset:46176
	s_waitcnt lgkmcnt(1)
	v_mfma_f32_32x32x16_bf16 v[16:31], v[46:49], v[50:53], v[16:31]
	ds_read_b128 v[46:49], v36 offset:23104
	s_waitcnt lgkmcnt(0)
	v_mfma_f32_32x32x16_bf16 v[0:15], v[46:49], v[50:53], v[0:15]
	ds_read_b128 v[46:49], v36 offset:18528
	ds_read_b128 v[36:39], v36 offset:23136
	s_waitcnt lgkmcnt(0)
	s_barrier
	v_mfma_f32_32x32x16_bf16 v[16:31], v[46:49], v[32:35], v[16:31]
	v_mfma_f32_32x32x16_bf16 v[0:15], v[36:39], v[32:35], v[0:15]
	v_readfirstlane_b32 s13, v186
	v_and_b32_e32 v32, 63, v186
	v_and_b32_e32 v33, 31, v32
	v_lshrrev_b32_e32 v34, 5, v32
	s_lshr_b32 s13, s13, 6
	s_and_b32 s32, s13, 1
	s_lshr_b32 s13, s13, 1
	s_lshl_b32 s13, s13, 6
	s_add_i32 s33, s41, 0xffffe000
	s_add_i32 s13, s13, s33
	v_lshl_add_u32 v35, v34, 2, s13
	s_cmp_lg_u32 s32, 0
	s_cbranch_scc1 .Lp3a_gate
	v_and_b32_e32 v36, 15, v33
	v_lshlrev_b32_e32 v37, 6, v35
	v_lshl_add_u32 v37, v36, 2, v37
	v_xor_b32_e32 v38, 16, v32
	v_lshlrev_b32_e32 v38, 2, v38
	global_load_dword v84, v37, s[0:1]
	global_load_dword v116, v37, s[8:9]
	global_load_dword v85, v37, s[0:1] offset:64
	global_load_dword v117, v37, s[8:9] offset:64
	global_load_dword v86, v37, s[0:1] offset:128
	global_load_dword v118, v37, s[8:9] offset:128
	global_load_dword v87, v37, s[0:1] offset:192
	global_load_dword v119, v37, s[8:9] offset:192
	global_load_dword v88, v37, s[0:1] offset:512
	global_load_dword v120, v37, s[8:9] offset:512
	global_load_dword v89, v37, s[0:1] offset:576
	global_load_dword v121, v37, s[8:9] offset:576
	global_load_dword v90, v37, s[0:1] offset:640
	global_load_dword v122, v37, s[8:9] offset:640
	global_load_dword v91, v37, s[0:1] offset:704
	global_load_dword v123, v37, s[8:9] offset:704
	global_load_dword v92, v37, s[0:1] offset:1024
	global_load_dword v124, v37, s[8:9] offset:1024
	global_load_dword v93, v37, s[0:1] offset:1088
	global_load_dword v125, v37, s[8:9] offset:1088
	global_load_dword v94, v37, s[0:1] offset:1152
	global_load_dword v126, v37, s[8:9] offset:1152
	global_load_dword v95, v37, s[0:1] offset:1216
	global_load_dword v127, v37, s[8:9] offset:1216
	global_load_dword v96, v37, s[0:1] offset:1536
	global_load_dword v128, v37, s[8:9] offset:1536
	global_load_dword v97, v37, s[0:1] offset:1600
	global_load_dword v129, v37, s[8:9] offset:1600
	global_load_dword v98, v37, s[0:1] offset:1664
	global_load_dword v130, v37, s[8:9] offset:1664
	global_load_dword v99, v37, s[0:1] offset:1728
	global_load_dword v131, v37, s[8:9] offset:1728
	global_load_dword v100, v37, s[0:1] offset:2048
	global_load_dword v132, v37, s[8:9] offset:2048
	global_load_dword v101, v37, s[0:1] offset:2112
	global_load_dword v133, v37, s[8:9] offset:2112
	global_load_dword v102, v37, s[0:1] offset:2176
	global_load_dword v134, v37, s[8:9] offset:2176
	global_load_dword v103, v37, s[0:1] offset:2240
	global_load_dword v135, v37, s[8:9] offset:2240
	global_load_dword v104, v37, s[0:1] offset:2560
	global_load_dword v136, v37, s[8:9] offset:2560
	global_load_dword v105, v37, s[0:1] offset:2624
	global_load_dword v137, v37, s[8:9] offset:2624
	global_load_dword v106, v37, s[0:1] offset:2688
	global_load_dword v138, v37, s[8:9] offset:2688
	global_load_dword v107, v37, s[0:1] offset:2752
	global_load_dword v139, v37, s[8:9] offset:2752
	global_load_dword v108, v37, s[0:1] offset:3072
	global_load_dword v140, v37, s[8:9] offset:3072
	global_load_dword v109, v37, s[0:1] offset:3136
	global_load_dword v141, v37, s[8:9] offset:3136
	global_load_dword v110, v37, s[0:1] offset:3200
	global_load_dword v142, v37, s[8:9] offset:3200
	global_load_dword v111, v37, s[0:1] offset:3264
	global_load_dword v143, v37, s[8:9] offset:3264
	global_load_dword v112, v37, s[0:1] offset:3584
	global_load_dword v144, v37, s[8:9] offset:3584
	global_load_dword v113, v37, s[0:1] offset:3648
	global_load_dword v145, v37, s[8:9] offset:3648
	global_load_dword v114, v37, s[0:1] offset:3712
	global_load_dword v146, v37, s[8:9] offset:3712
	global_load_dword v115, v37, s[0:1] offset:3776
	global_load_dword v147, v37, s[8:9] offset:3776
	v_and_b32_e32 v39, 0x1fff, v35
	v_mul_u32_u24_e32 v39, 0xc0, v39
	v_lshl_add_u32 v39, v33, 1, v39
	v_add_u32_e32 v39, 0x80, v39
	s_lshr_b32 s13, s33, 13
	s_mul_i32 s13, s13, 0xc00000
	s_add_u32 s13, s13, 0xb200000
	s_add_u32 s78, s88, s13
	s_addc_u32 s79, s89, 0
	ds_bpermute_b32 v148, v38, v16
	ds_bpermute_b32 v149, v38, v17
	ds_bpermute_b32 v150, v38, v18
	ds_bpermute_b32 v151, v38, v19
	ds_bpermute_b32 v152, v38, v20
	ds_bpermute_b32 v153, v38, v21
	ds_bpermute_b32 v154, v38, v22
	ds_bpermute_b32 v155, v38, v23
	s_waitcnt vmcnt(0) lgkmcnt(0)
	v_mul_f32_e32 v46, v116, v148
	v_cndmask_b32_e64 v46, v46, -v46, s[6:7]
	v_fmac_f32_e32 v46, v16, v84
	v_cvt_pk_bf16_f32 v46, v46, v46
	v_mov_b32_e32 v47, v39
	global_store_short v47, v46, s[78:79]
	v_add_u32_e32 v49, 0x180000, v47
	global_store_short v49, v46, s[78:79]
	v_add_u32_e32 v48, 0x300000, v47
	global_store_short v48, v46, s[78:79]
	v_add_u32_e32 v49, 0x480000, v47
	global_store_short v49, v46, s[78:79]
	v_add_u32_e32 v48, 0x600000, v47
	global_store_short v48, v46, s[78:79]
	v_add_u32_e32 v49, 0x780000, v47
	global_store_short v49, v46, s[78:79]
	v_add_u32_e32 v48, 0x900000, v47
	global_store_short v48, v46, s[78:79]
	v_add_u32_e32 v49, 0xa80000, v47
	global_store_short v49, v46, s[78:79]
	v_mul_f32_e32 v50, v117, v149
	v_cndmask_b32_e64 v50, v50, -v50, s[6:7]
	v_fmac_f32_e32 v50, v17, v85
	v_cvt_pk_bf16_f32 v50, v50, v50
	v_add_u32_e32 v51, 0xc0, v39
	global_store_short v51, v50, s[78:79]
	v_add_u32_e32 v53, 0x180000, v51
	global_store_short v53, v50, s[78:79]
	v_add_u32_e32 v52, 0x300000, v51
	global_store_short v52, v50, s[78:79]
	v_add_u32_e32 v53, 0x480000, v51
	global_store_short v53, v50, s[78:79]
	v_add_u32_e32 v52, 0x600000, v51
	global_store_short v52, v50, s[78:79]
	v_add_u32_e32 v53, 0x780000, v51
	global_store_short v53, v50, s[78:79]
	v_add_u32_e32 v52, 0x900000, v51
	global_store_short v52, v50, s[78:79]
	v_add_u32_e32 v53, 0xa80000, v51
	global_store_short v53, v50, s[78:79]
	v_mul_f32_e32 v46, v118, v150
	v_cndmask_b32_e64 v46, v46, -v46, s[6:7]
	v_fmac_f32_e32 v46, v18, v86
	v_cvt_pk_bf16_f32 v46, v46, v46
	v_add_u32_e32 v47, 0x180, v39
	global_store_short v47, v46, s[78:79]
	v_add_u32_e32 v49, 0x180000, v47
	global_store_short v49, v46, s[78:79]
	v_add_u32_e32 v48, 0x300000, v47
	global_store_short v48, v46, s[78:79]
	v_add_u32_e32 v49, 0x480000, v47
	global_store_short v49, v46, s[78:79]
	v_add_u32_e32 v48, 0x600000, v47
	global_store_short v48, v46, s[78:79]
	v_add_u32_e32 v49, 0x780000, v47
	global_store_short v49, v46, s[78:79]
	v_add_u32_e32 v48, 0x900000, v47
	global_store_short v48, v46, s[78:79]
	v_add_u32_e32 v49, 0xa80000, v47
	global_store_short v49, v46, s[78:79]
	v_mul_f32_e32 v50, v119, v151
	v_cndmask_b32_e64 v50, v50, -v50, s[6:7]
	v_fmac_f32_e32 v50, v19, v87
	v_cvt_pk_bf16_f32 v50, v50, v50
	v_add_u32_e32 v51, 0x240, v39
	global_store_short v51, v50, s[78:79]
	v_add_u32_e32 v53, 0x180000, v51
	global_store_short v53, v50, s[78:79]
	v_add_u32_e32 v52, 0x300000, v51
	global_store_short v52, v50, s[78:79]
	v_add_u32_e32 v53, 0x480000, v51
	global_store_short v53, v50, s[78:79]
	v_add_u32_e32 v52, 0x600000, v51
	global_store_short v52, v50, s[78:79]
	v_add_u32_e32 v53, 0x780000, v51
	global_store_short v53, v50, s[78:79]
	v_add_u32_e32 v52, 0x900000, v51
	global_store_short v52, v50, s[78:79]
	v_add_u32_e32 v53, 0xa80000, v51
	global_store_short v53, v50, s[78:79]
	v_mul_f32_e32 v46, v120, v152
	v_cndmask_b32_e64 v46, v46, -v46, s[6:7]
	v_fmac_f32_e32 v46, v20, v88
	v_cvt_pk_bf16_f32 v46, v46, v46
	v_add_u32_e32 v47, 0x600, v39
	global_store_short v47, v46, s[78:79]
	v_add_u32_e32 v49, 0x180000, v47
	global_store_short v49, v46, s[78:79]
	v_add_u32_e32 v48, 0x300000, v47
	global_store_short v48, v46, s[78:79]
	v_add_u32_e32 v49, 0x480000, v47
	global_store_short v49, v46, s[78:79]
	v_add_u32_e32 v48, 0x600000, v47
	global_store_short v48, v46, s[78:79]
	v_add_u32_e32 v49, 0x780000, v47
	global_store_short v49, v46, s[78:79]
	v_add_u32_e32 v48, 0x900000, v47
	global_store_short v48, v46, s[78:79]
	v_add_u32_e32 v49, 0xa80000, v47
	global_store_short v49, v46, s[78:79]
	v_mul_f32_e32 v50, v121, v153
	v_cndmask_b32_e64 v50, v50, -v50, s[6:7]
	v_fmac_f32_e32 v50, v21, v89
	v_cvt_pk_bf16_f32 v50, v50, v50
	v_add_u32_e32 v51, 0x6c0, v39
	global_store_short v51, v50, s[78:79]
	v_add_u32_e32 v53, 0x180000, v51
	global_store_short v53, v50, s[78:79]
	v_add_u32_e32 v52, 0x300000, v51
	global_store_short v52, v50, s[78:79]
	v_add_u32_e32 v53, 0x480000, v51
	global_store_short v53, v50, s[78:79]
	v_add_u32_e32 v52, 0x600000, v51
	global_store_short v52, v50, s[78:79]
	v_add_u32_e32 v53, 0x780000, v51
	global_store_short v53, v50, s[78:79]
	v_add_u32_e32 v52, 0x900000, v51
	global_store_short v52, v50, s[78:79]
	v_add_u32_e32 v53, 0xa80000, v51
	global_store_short v53, v50, s[78:79]
	v_mul_f32_e32 v46, v122, v154
	v_cndmask_b32_e64 v46, v46, -v46, s[6:7]
	v_fmac_f32_e32 v46, v22, v90
	v_cvt_pk_bf16_f32 v46, v46, v46
	v_add_u32_e32 v47, 0x780, v39
	global_store_short v47, v46, s[78:79]
	v_add_u32_e32 v49, 0x180000, v47
	global_store_short v49, v46, s[78:79]
	v_add_u32_e32 v48, 0x300000, v47
	global_store_short v48, v46, s[78:79]
	v_add_u32_e32 v49, 0x480000, v47
	global_store_short v49, v46, s[78:79]
	v_add_u32_e32 v48, 0x600000, v47
	global_store_short v48, v46, s[78:79]
	v_add_u32_e32 v49, 0x780000, v47
	global_store_short v49, v46, s[78:79]
	v_add_u32_e32 v48, 0x900000, v47
	global_store_short v48, v46, s[78:79]
	v_add_u32_e32 v49, 0xa80000, v47
	global_store_short v49, v46, s[78:79]
	v_mul_f32_e32 v50, v123, v155
	v_cndmask_b32_e64 v50, v50, -v50, s[6:7]
	v_fmac_f32_e32 v50, v23, v91
	v_cvt_pk_bf16_f32 v50, v50, v50
	v_add_u32_e32 v51, 0x840, v39
	global_store_short v51, v50, s[78:79]
	v_add_u32_e32 v53, 0x180000, v51
	global_store_short v53, v50, s[78:79]
	v_add_u32_e32 v52, 0x300000, v51
	global_store_short v52, v50, s[78:79]
	v_add_u32_e32 v53, 0x480000, v51
	global_store_short v53, v50, s[78:79]
	v_add_u32_e32 v52, 0x600000, v51
	global_store_short v52, v50, s[78:79]
	v_add_u32_e32 v53, 0x780000, v51
	global_store_short v53, v50, s[78:79]
	v_add_u32_e32 v52, 0x900000, v51
	global_store_short v52, v50, s[78:79]
	v_add_u32_e32 v53, 0xa80000, v51
	global_store_short v53, v50, s[78:79]
	ds_bpermute_b32 v148, v38, v24
	ds_bpermute_b32 v149, v38, v25
	ds_bpermute_b32 v150, v38, v26
	ds_bpermute_b32 v151, v38, v27
	ds_bpermute_b32 v152, v38, v28
	ds_bpermute_b32 v153, v38, v29
	ds_bpermute_b32 v154, v38, v30
	ds_bpermute_b32 v155, v38, v31
	s_waitcnt lgkmcnt(0)
	v_mul_f32_e32 v46, v124, v148
	v_cndmask_b32_e64 v46, v46, -v46, s[6:7]
	v_fmac_f32_e32 v46, v24, v92
	v_cvt_pk_bf16_f32 v46, v46, v46
	v_add_u32_e32 v47, 0xc00, v39
	global_store_short v47, v46, s[78:79]
	v_add_u32_e32 v49, 0x180000, v47
	global_store_short v49, v46, s[78:79]
	v_add_u32_e32 v48, 0x300000, v47
	global_store_short v48, v46, s[78:79]
	v_add_u32_e32 v49, 0x480000, v47
	global_store_short v49, v46, s[78:79]
	v_add_u32_e32 v48, 0x600000, v47
	global_store_short v48, v46, s[78:79]
	v_add_u32_e32 v49, 0x780000, v47
	global_store_short v49, v46, s[78:79]
	v_add_u32_e32 v48, 0x900000, v47
	global_store_short v48, v46, s[78:79]
	v_add_u32_e32 v49, 0xa80000, v47
	global_store_short v49, v46, s[78:79]
	v_mul_f32_e32 v50, v125, v149
	v_cndmask_b32_e64 v50, v50, -v50, s[6:7]
	v_fmac_f32_e32 v50, v25, v93
	v_cvt_pk_bf16_f32 v50, v50, v50
	v_add_u32_e32 v51, 0xcc0, v39
	global_store_short v51, v50, s[78:79]
	v_add_u32_e32 v53, 0x180000, v51
	global_store_short v53, v50, s[78:79]
	v_add_u32_e32 v52, 0x300000, v51
	global_store_short v52, v50, s[78:79]
	v_add_u32_e32 v53, 0x480000, v51
	global_store_short v53, v50, s[78:79]
	v_add_u32_e32 v52, 0x600000, v51
	global_store_short v52, v50, s[78:79]
	v_add_u32_e32 v53, 0x780000, v51
	global_store_short v53, v50, s[78:79]
	v_add_u32_e32 v52, 0x900000, v51
	global_store_short v52, v50, s[78:79]
	v_add_u32_e32 v53, 0xa80000, v51
	global_store_short v53, v50, s[78:79]
	v_mul_f32_e32 v46, v126, v150
	v_cndmask_b32_e64 v46, v46, -v46, s[6:7]
	v_fmac_f32_e32 v46, v26, v94
	v_cvt_pk_bf16_f32 v46, v46, v46
	v_add_u32_e32 v47, 0xd80, v39
	global_store_short v47, v46, s[78:79]
	v_add_u32_e32 v49, 0x180000, v47
	global_store_short v49, v46, s[78:79]
	v_add_u32_e32 v48, 0x300000, v47
	global_store_short v48, v46, s[78:79]
	v_add_u32_e32 v49, 0x480000, v47
	global_store_short v49, v46, s[78:79]
	v_add_u32_e32 v48, 0x600000, v47
	global_store_short v48, v46, s[78:79]
	v_add_u32_e32 v49, 0x780000, v47
	global_store_short v49, v46, s[78:79]
	v_add_u32_e32 v48, 0x900000, v47
	global_store_short v48, v46, s[78:79]
	v_add_u32_e32 v49, 0xa80000, v47
	global_store_short v49, v46, s[78:79]
	v_mul_f32_e32 v50, v127, v151
	v_cndmask_b32_e64 v50, v50, -v50, s[6:7]
	v_fmac_f32_e32 v50, v27, v95
	v_cvt_pk_bf16_f32 v50, v50, v50
	v_add_u32_e32 v51, 0xe40, v39
	global_store_short v51, v50, s[78:79]
	v_add_u32_e32 v53, 0x180000, v51
	global_store_short v53, v50, s[78:79]
	v_add_u32_e32 v52, 0x300000, v51
	global_store_short v52, v50, s[78:79]
	v_add_u32_e32 v53, 0x480000, v51
	global_store_short v53, v50, s[78:79]
	v_add_u32_e32 v52, 0x600000, v51
	global_store_short v52, v50, s[78:79]
	v_add_u32_e32 v53, 0x780000, v51
	global_store_short v53, v50, s[78:79]
	v_add_u32_e32 v52, 0x900000, v51
	global_store_short v52, v50, s[78:79]
	v_add_u32_e32 v53, 0xa80000, v51
	global_store_short v53, v50, s[78:79]
	v_mul_f32_e32 v46, v128, v152
	v_cndmask_b32_e64 v46, v46, -v46, s[6:7]
	v_fmac_f32_e32 v46, v28, v96
	v_cvt_pk_bf16_f32 v46, v46, v46
	v_add_u32_e32 v47, 0x1200, v39
	global_store_short v47, v46, s[78:79]
	v_add_u32_e32 v49, 0x180000, v47
	global_store_short v49, v46, s[78:79]
	v_add_u32_e32 v48, 0x300000, v47
	global_store_short v48, v46, s[78:79]
	v_add_u32_e32 v49, 0x480000, v47
	global_store_short v49, v46, s[78:79]
	v_add_u32_e32 v48, 0x600000, v47
	global_store_short v48, v46, s[78:79]
	v_add_u32_e32 v49, 0x780000, v47
	global_store_short v49, v46, s[78:79]
	v_add_u32_e32 v48, 0x900000, v47
	global_store_short v48, v46, s[78:79]
	v_add_u32_e32 v49, 0xa80000, v47
	global_store_short v49, v46, s[78:79]
	v_mul_f32_e32 v50, v129, v153
	v_cndmask_b32_e64 v50, v50, -v50, s[6:7]
	v_fmac_f32_e32 v50, v29, v97
	v_cvt_pk_bf16_f32 v50, v50, v50
	v_add_u32_e32 v51, 0x12c0, v39
	global_store_short v51, v50, s[78:79]
	v_add_u32_e32 v53, 0x180000, v51
	global_store_short v53, v50, s[78:79]
	v_add_u32_e32 v52, 0x300000, v51
	global_store_short v52, v50, s[78:79]
	v_add_u32_e32 v53, 0x480000, v51
	global_store_short v53, v50, s[78:79]
	v_add_u32_e32 v52, 0x600000, v51
	global_store_short v52, v50, s[78:79]
	v_add_u32_e32 v53, 0x780000, v51
	global_store_short v53, v50, s[78:79]
	v_add_u32_e32 v52, 0x900000, v51
	global_store_short v52, v50, s[78:79]
	v_add_u32_e32 v53, 0xa80000, v51
	global_store_short v53, v50, s[78:79]
	v_mul_f32_e32 v46, v130, v154
	v_cndmask_b32_e64 v46, v46, -v46, s[6:7]
	v_fmac_f32_e32 v46, v30, v98
	v_cvt_pk_bf16_f32 v46, v46, v46
	v_add_u32_e32 v47, 0x1380, v39
	global_store_short v47, v46, s[78:79]
	v_add_u32_e32 v49, 0x180000, v47
	global_store_short v49, v46, s[78:79]
	v_add_u32_e32 v48, 0x300000, v47
	global_store_short v48, v46, s[78:79]
	v_add_u32_e32 v49, 0x480000, v47
	global_store_short v49, v46, s[78:79]
	v_add_u32_e32 v48, 0x600000, v47
	global_store_short v48, v46, s[78:79]
	v_add_u32_e32 v49, 0x780000, v47
	global_store_short v49, v46, s[78:79]
	v_add_u32_e32 v48, 0x900000, v47
	global_store_short v48, v46, s[78:79]
	v_add_u32_e32 v49, 0xa80000, v47
	global_store_short v49, v46, s[78:79]
	v_mul_f32_e32 v50, v131, v155
	v_cndmask_b32_e64 v50, v50, -v50, s[6:7]
	v_fmac_f32_e32 v50, v31, v99
	v_cvt_pk_bf16_f32 v50, v50, v50
	v_add_u32_e32 v51, 0x1440, v39
	global_store_short v51, v50, s[78:79]
	v_add_u32_e32 v53, 0x180000, v51
	global_store_short v53, v50, s[78:79]
	v_add_u32_e32 v52, 0x300000, v51
	global_store_short v52, v50, s[78:79]
	v_add_u32_e32 v53, 0x480000, v51
	global_store_short v53, v50, s[78:79]
	v_add_u32_e32 v52, 0x600000, v51
	global_store_short v52, v50, s[78:79]
	v_add_u32_e32 v53, 0x780000, v51
	global_store_short v53, v50, s[78:79]
	v_add_u32_e32 v52, 0x900000, v51
	global_store_short v52, v50, s[78:79]
	v_add_u32_e32 v53, 0xa80000, v51
	global_store_short v53, v50, s[78:79]
	ds_bpermute_b32 v148, v38, v0
	ds_bpermute_b32 v149, v38, v1
	ds_bpermute_b32 v150, v38, v2
	ds_bpermute_b32 v151, v38, v3
	ds_bpermute_b32 v152, v38, v4
	ds_bpermute_b32 v153, v38, v5
	ds_bpermute_b32 v154, v38, v6
	ds_bpermute_b32 v155, v38, v7
	s_waitcnt lgkmcnt(0)
	v_mul_f32_e32 v46, v132, v148
	v_cndmask_b32_e64 v46, v46, -v46, s[6:7]
	v_fmac_f32_e32 v46, v0, v100
	v_cvt_pk_bf16_f32 v46, v46, v46
	v_add_u32_e32 v47, 0x1800, v39
	global_store_short v47, v46, s[78:79]
	v_add_u32_e32 v49, 0x180000, v47
	global_store_short v49, v46, s[78:79]
	v_add_u32_e32 v48, 0x300000, v47
	global_store_short v48, v46, s[78:79]
	v_add_u32_e32 v49, 0x480000, v47
	global_store_short v49, v46, s[78:79]
	v_add_u32_e32 v48, 0x600000, v47
	global_store_short v48, v46, s[78:79]
	v_add_u32_e32 v49, 0x780000, v47
	global_store_short v49, v46, s[78:79]
	v_add_u32_e32 v48, 0x900000, v47
	global_store_short v48, v46, s[78:79]
	v_add_u32_e32 v49, 0xa80000, v47
	global_store_short v49, v46, s[78:79]
	v_mul_f32_e32 v50, v133, v149
	v_cndmask_b32_e64 v50, v50, -v50, s[6:7]
	v_fmac_f32_e32 v50, v1, v101
	v_cvt_pk_bf16_f32 v50, v50, v50
	v_add_u32_e32 v51, 0x18c0, v39
	global_store_short v51, v50, s[78:79]
	v_add_u32_e32 v53, 0x180000, v51
	global_store_short v53, v50, s[78:79]
	v_add_u32_e32 v52, 0x300000, v51
	global_store_short v52, v50, s[78:79]
	v_add_u32_e32 v53, 0x480000, v51
	global_store_short v53, v50, s[78:79]
	v_add_u32_e32 v52, 0x600000, v51
	global_store_short v52, v50, s[78:79]
	v_add_u32_e32 v53, 0x780000, v51
	global_store_short v53, v50, s[78:79]
	v_add_u32_e32 v52, 0x900000, v51
	global_store_short v52, v50, s[78:79]
	v_add_u32_e32 v53, 0xa80000, v51
	global_store_short v53, v50, s[78:79]
	v_mul_f32_e32 v46, v134, v150
	v_cndmask_b32_e64 v46, v46, -v46, s[6:7]
	v_fmac_f32_e32 v46, v2, v102
	v_cvt_pk_bf16_f32 v46, v46, v46
	v_add_u32_e32 v47, 0x1980, v39
	global_store_short v47, v46, s[78:79]
	v_add_u32_e32 v49, 0x180000, v47
	global_store_short v49, v46, s[78:79]
	v_add_u32_e32 v48, 0x300000, v47
	global_store_short v48, v46, s[78:79]
	v_add_u32_e32 v49, 0x480000, v47
	global_store_short v49, v46, s[78:79]
	v_add_u32_e32 v48, 0x600000, v47
	global_store_short v48, v46, s[78:79]
	v_add_u32_e32 v49, 0x780000, v47
	global_store_short v49, v46, s[78:79]
	v_add_u32_e32 v48, 0x900000, v47
	global_store_short v48, v46, s[78:79]
	v_add_u32_e32 v49, 0xa80000, v47
	global_store_short v49, v46, s[78:79]
	v_mul_f32_e32 v50, v135, v151
	v_cndmask_b32_e64 v50, v50, -v50, s[6:7]
	v_fmac_f32_e32 v50, v3, v103
	v_cvt_pk_bf16_f32 v50, v50, v50
	v_add_u32_e32 v51, 0x1a40, v39
	global_store_short v51, v50, s[78:79]
	v_add_u32_e32 v53, 0x180000, v51
	global_store_short v53, v50, s[78:79]
	v_add_u32_e32 v52, 0x300000, v51
	global_store_short v52, v50, s[78:79]
	v_add_u32_e32 v53, 0x480000, v51
	global_store_short v53, v50, s[78:79]
	v_add_u32_e32 v52, 0x600000, v51
	global_store_short v52, v50, s[78:79]
	v_add_u32_e32 v53, 0x780000, v51
	global_store_short v53, v50, s[78:79]
	v_add_u32_e32 v52, 0x900000, v51
	global_store_short v52, v50, s[78:79]
	v_add_u32_e32 v53, 0xa80000, v51
	global_store_short v53, v50, s[78:79]
	v_mul_f32_e32 v46, v136, v152
	v_cndmask_b32_e64 v46, v46, -v46, s[6:7]
	v_fmac_f32_e32 v46, v4, v104
	v_cvt_pk_bf16_f32 v46, v46, v46
	v_add_u32_e32 v47, 0x1e00, v39
	global_store_short v47, v46, s[78:79]
	v_add_u32_e32 v49, 0x180000, v47
	global_store_short v49, v46, s[78:79]
	v_add_u32_e32 v48, 0x300000, v47
	global_store_short v48, v46, s[78:79]
	v_add_u32_e32 v49, 0x480000, v47
	global_store_short v49, v46, s[78:79]
	v_add_u32_e32 v48, 0x600000, v47
	global_store_short v48, v46, s[78:79]
	v_add_u32_e32 v49, 0x780000, v47
	global_store_short v49, v46, s[78:79]
	v_add_u32_e32 v48, 0x900000, v47
	global_store_short v48, v46, s[78:79]
	v_add_u32_e32 v49, 0xa80000, v47
	global_store_short v49, v46, s[78:79]
	v_mul_f32_e32 v50, v137, v153
	v_cndmask_b32_e64 v50, v50, -v50, s[6:7]
	v_fmac_f32_e32 v50, v5, v105
	v_cvt_pk_bf16_f32 v50, v50, v50
	v_add_u32_e32 v51, 0x1ec0, v39
	global_store_short v51, v50, s[78:79]
	v_add_u32_e32 v53, 0x180000, v51
	global_store_short v53, v50, s[78:79]
	v_add_u32_e32 v52, 0x300000, v51
	global_store_short v52, v50, s[78:79]
	v_add_u32_e32 v53, 0x480000, v51
	global_store_short v53, v50, s[78:79]
	v_add_u32_e32 v52, 0x600000, v51
	global_store_short v52, v50, s[78:79]
	v_add_u32_e32 v53, 0x780000, v51
	global_store_short v53, v50, s[78:79]
	v_add_u32_e32 v52, 0x900000, v51
	global_store_short v52, v50, s[78:79]
	v_add_u32_e32 v53, 0xa80000, v51
	global_store_short v53, v50, s[78:79]
	v_mul_f32_e32 v46, v138, v154
	v_cndmask_b32_e64 v46, v46, -v46, s[6:7]
	v_fmac_f32_e32 v46, v6, v106
	v_cvt_pk_bf16_f32 v46, v46, v46
	v_add_u32_e32 v47, 0x1f80, v39
	global_store_short v47, v46, s[78:79]
	v_add_u32_e32 v49, 0x180000, v47
	global_store_short v49, v46, s[78:79]
	v_add_u32_e32 v48, 0x300000, v47
	global_store_short v48, v46, s[78:79]
	v_add_u32_e32 v49, 0x480000, v47
	global_store_short v49, v46, s[78:79]
	v_add_u32_e32 v48, 0x600000, v47
	global_store_short v48, v46, s[78:79]
	v_add_u32_e32 v49, 0x780000, v47
	global_store_short v49, v46, s[78:79]
	v_add_u32_e32 v48, 0x900000, v47
	global_store_short v48, v46, s[78:79]
	v_add_u32_e32 v49, 0xa80000, v47
	global_store_short v49, v46, s[78:79]
	v_mul_f32_e32 v50, v139, v155
	v_cndmask_b32_e64 v50, v50, -v50, s[6:7]
	v_fmac_f32_e32 v50, v7, v107
	v_cvt_pk_bf16_f32 v50, v50, v50
	v_add_u32_e32 v51, 0x2040, v39
	global_store_short v51, v50, s[78:79]
	v_add_u32_e32 v53, 0x180000, v51
	global_store_short v53, v50, s[78:79]
	v_add_u32_e32 v52, 0x300000, v51
	global_store_short v52, v50, s[78:79]
	v_add_u32_e32 v53, 0x480000, v51
	global_store_short v53, v50, s[78:79]
	v_add_u32_e32 v52, 0x600000, v51
	global_store_short v52, v50, s[78:79]
	v_add_u32_e32 v53, 0x780000, v51
	global_store_short v53, v50, s[78:79]
	v_add_u32_e32 v52, 0x900000, v51
	global_store_short v52, v50, s[78:79]
	v_add_u32_e32 v53, 0xa80000, v51
	global_store_short v53, v50, s[78:79]
	ds_bpermute_b32 v148, v38, v8
	ds_bpermute_b32 v149, v38, v9
	ds_bpermute_b32 v150, v38, v10
	ds_bpermute_b32 v151, v38, v11
	ds_bpermute_b32 v152, v38, v12
	ds_bpermute_b32 v153, v38, v13
	ds_bpermute_b32 v154, v38, v14
	ds_bpermute_b32 v155, v38, v15
	s_waitcnt lgkmcnt(0)
	v_mul_f32_e32 v46, v140, v148
	v_cndmask_b32_e64 v46, v46, -v46, s[6:7]
	v_fmac_f32_e32 v46, v8, v108
	v_cvt_pk_bf16_f32 v46, v46, v46
	v_add_u32_e32 v47, 0x2400, v39
	global_store_short v47, v46, s[78:79]
	v_add_u32_e32 v49, 0x180000, v47
	global_store_short v49, v46, s[78:79]
	v_add_u32_e32 v48, 0x300000, v47
	global_store_short v48, v46, s[78:79]
	v_add_u32_e32 v49, 0x480000, v47
	global_store_short v49, v46, s[78:79]
	v_add_u32_e32 v48, 0x600000, v47
	global_store_short v48, v46, s[78:79]
	v_add_u32_e32 v49, 0x780000, v47
	global_store_short v49, v46, s[78:79]
	v_add_u32_e32 v48, 0x900000, v47
	global_store_short v48, v46, s[78:79]
	v_add_u32_e32 v49, 0xa80000, v47
	global_store_short v49, v46, s[78:79]
	v_mul_f32_e32 v50, v141, v149
	v_cndmask_b32_e64 v50, v50, -v50, s[6:7]
	v_fmac_f32_e32 v50, v9, v109
	v_cvt_pk_bf16_f32 v50, v50, v50
	v_add_u32_e32 v51, 0x24c0, v39
	global_store_short v51, v50, s[78:79]
	v_add_u32_e32 v53, 0x180000, v51
	global_store_short v53, v50, s[78:79]
	v_add_u32_e32 v52, 0x300000, v51
	global_store_short v52, v50, s[78:79]
	v_add_u32_e32 v53, 0x480000, v51
	global_store_short v53, v50, s[78:79]
	v_add_u32_e32 v52, 0x600000, v51
	global_store_short v52, v50, s[78:79]
	v_add_u32_e32 v53, 0x780000, v51
	global_store_short v53, v50, s[78:79]
	v_add_u32_e32 v52, 0x900000, v51
	global_store_short v52, v50, s[78:79]
	v_add_u32_e32 v53, 0xa80000, v51
	global_store_short v53, v50, s[78:79]
	v_mul_f32_e32 v46, v142, v150
	v_cndmask_b32_e64 v46, v46, -v46, s[6:7]
	v_fmac_f32_e32 v46, v10, v110
	v_cvt_pk_bf16_f32 v46, v46, v46
	v_add_u32_e32 v47, 0x2580, v39
	global_store_short v47, v46, s[78:79]
	v_add_u32_e32 v49, 0x180000, v47
	global_store_short v49, v46, s[78:79]
	v_add_u32_e32 v48, 0x300000, v47
	global_store_short v48, v46, s[78:79]
	v_add_u32_e32 v49, 0x480000, v47
	global_store_short v49, v46, s[78:79]
	v_add_u32_e32 v48, 0x600000, v47
	global_store_short v48, v46, s[78:79]
	v_add_u32_e32 v49, 0x780000, v47
	global_store_short v49, v46, s[78:79]
	v_add_u32_e32 v48, 0x900000, v47
	global_store_short v48, v46, s[78:79]
	v_add_u32_e32 v49, 0xa80000, v47
	global_store_short v49, v46, s[78:79]
	v_mul_f32_e32 v50, v143, v151
	v_cndmask_b32_e64 v50, v50, -v50, s[6:7]
	v_fmac_f32_e32 v50, v11, v111
	v_cvt_pk_bf16_f32 v50, v50, v50
	v_add_u32_e32 v51, 0x2640, v39
	global_store_short v51, v50, s[78:79]
	v_add_u32_e32 v53, 0x180000, v51
	global_store_short v53, v50, s[78:79]
	v_add_u32_e32 v52, 0x300000, v51
	global_store_short v52, v50, s[78:79]
	v_add_u32_e32 v53, 0x480000, v51
	global_store_short v53, v50, s[78:79]
	v_add_u32_e32 v52, 0x600000, v51
	global_store_short v52, v50, s[78:79]
	v_add_u32_e32 v53, 0x780000, v51
	global_store_short v53, v50, s[78:79]
	v_add_u32_e32 v52, 0x900000, v51
	global_store_short v52, v50, s[78:79]
	v_add_u32_e32 v53, 0xa80000, v51
	global_store_short v53, v50, s[78:79]
	v_mul_f32_e32 v46, v144, v152
	v_cndmask_b32_e64 v46, v46, -v46, s[6:7]
	v_fmac_f32_e32 v46, v12, v112
	v_cvt_pk_bf16_f32 v46, v46, v46
	v_add_u32_e32 v47, 0x2a00, v39
	global_store_short v47, v46, s[78:79]
	v_add_u32_e32 v49, 0x180000, v47
	global_store_short v49, v46, s[78:79]
	v_add_u32_e32 v48, 0x300000, v47
	global_store_short v48, v46, s[78:79]
	v_add_u32_e32 v49, 0x480000, v47
	global_store_short v49, v46, s[78:79]
	v_add_u32_e32 v48, 0x600000, v47
	global_store_short v48, v46, s[78:79]
	v_add_u32_e32 v49, 0x780000, v47
	global_store_short v49, v46, s[78:79]
	v_add_u32_e32 v48, 0x900000, v47
	global_store_short v48, v46, s[78:79]
	v_add_u32_e32 v49, 0xa80000, v47
	global_store_short v49, v46, s[78:79]
	v_mul_f32_e32 v50, v145, v153
	v_cndmask_b32_e64 v50, v50, -v50, s[6:7]
	v_fmac_f32_e32 v50, v13, v113
	v_cvt_pk_bf16_f32 v50, v50, v50
	v_add_u32_e32 v51, 0x2ac0, v39
	global_store_short v51, v50, s[78:79]
	v_add_u32_e32 v53, 0x180000, v51
	global_store_short v53, v50, s[78:79]
	v_add_u32_e32 v52, 0x300000, v51
	global_store_short v52, v50, s[78:79]
	v_add_u32_e32 v53, 0x480000, v51
	global_store_short v53, v50, s[78:79]
	v_add_u32_e32 v52, 0x600000, v51
	global_store_short v52, v50, s[78:79]
	v_add_u32_e32 v53, 0x780000, v51
	global_store_short v53, v50, s[78:79]
	v_add_u32_e32 v52, 0x900000, v51
	global_store_short v52, v50, s[78:79]
	v_add_u32_e32 v53, 0xa80000, v51
	global_store_short v53, v50, s[78:79]
	v_mul_f32_e32 v46, v146, v154
	v_cndmask_b32_e64 v46, v46, -v46, s[6:7]
	v_fmac_f32_e32 v46, v14, v114
	v_cvt_pk_bf16_f32 v46, v46, v46
	v_add_u32_e32 v47, 0x2b80, v39
	global_store_short v47, v46, s[78:79]
	v_add_u32_e32 v49, 0x180000, v47
	global_store_short v49, v46, s[78:79]
	v_add_u32_e32 v48, 0x300000, v47
	global_store_short v48, v46, s[78:79]
	v_add_u32_e32 v49, 0x480000, v47
	global_store_short v49, v46, s[78:79]
	v_add_u32_e32 v48, 0x600000, v47
	global_store_short v48, v46, s[78:79]
	v_add_u32_e32 v49, 0x780000, v47
	global_store_short v49, v46, s[78:79]
	v_add_u32_e32 v48, 0x900000, v47
	global_store_short v48, v46, s[78:79]
	v_add_u32_e32 v49, 0xa80000, v47
	global_store_short v49, v46, s[78:79]
	v_mul_f32_e32 v50, v147, v155
	v_cndmask_b32_e64 v50, v50, -v50, s[6:7]
	v_fmac_f32_e32 v50, v15, v115
	v_cvt_pk_bf16_f32 v50, v50, v50
	v_add_u32_e32 v51, 0x2c40, v39
	global_store_short v51, v50, s[78:79]
	v_add_u32_e32 v53, 0x180000, v51
	global_store_short v53, v50, s[78:79]
	v_add_u32_e32 v52, 0x300000, v51
	global_store_short v52, v50, s[78:79]
	v_add_u32_e32 v53, 0x480000, v51
	global_store_short v53, v50, s[78:79]
	v_add_u32_e32 v52, 0x600000, v51
	global_store_short v52, v50, s[78:79]
	v_add_u32_e32 v53, 0x780000, v51
	global_store_short v53, v50, s[78:79]
	v_add_u32_e32 v52, 0x900000, v51
	global_store_short v52, v50, s[78:79]
	v_add_u32_e32 v53, 0xa80000, v51
	global_store_short v53, v50, s[78:79]
	s_branch .Lp3a_done
.Lp3a_gate:
	v_mul_u32_u24_e32 v36, 0x60, v35
	v_lshl_add_u32 v36, v33, 2, v36
	v_add_u32_e32 v37, 0xc00, v36
	s_add_u32 s80, s88, 0x9800000
	s_addc_u32 s81, s89, 0
	v_mul_f32_e32 v84, 0xbfb8aa3b, v16
	v_mul_f32_e32 v85, 0xbfb8aa3b, v17
	v_mul_f32_e32 v86, 0xbfb8aa3b, v18
	v_mul_f32_e32 v87, 0xbfb8aa3b, v19
	v_mul_f32_e32 v88, 0xbfb8aa3b, v20
	v_mul_f32_e32 v89, 0xbfb8aa3b, v21
	v_mul_f32_e32 v90, 0xbfb8aa3b, v22
	v_mul_f32_e32 v91, 0xbfb8aa3b, v23
	v_mul_f32_e32 v92, 0xbfb8aa3b, v24
	v_mul_f32_e32 v93, 0xbfb8aa3b, v25
	v_mul_f32_e32 v94, 0xbfb8aa3b, v26
	v_mul_f32_e32 v95, 0xbfb8aa3b, v27
	v_mul_f32_e32 v96, 0xbfb8aa3b, v28
	v_mul_f32_e32 v97, 0xbfb8aa3b, v29
	v_mul_f32_e32 v98, 0xbfb8aa3b, v30
	v_mul_f32_e32 v99, 0xbfb8aa3b, v31
	v_mul_f32_e32 v100, 0xbfb8aa3b, v0
	v_mul_f32_e32 v101, 0xbfb8aa3b, v1
	v_mul_f32_e32 v102, 0xbfb8aa3b, v2
	v_mul_f32_e32 v103, 0xbfb8aa3b, v3
	v_mul_f32_e32 v104, 0xbfb8aa3b, v4
	v_mul_f32_e32 v105, 0xbfb8aa3b, v5
	v_mul_f32_e32 v106, 0xbfb8aa3b, v6
	v_mul_f32_e32 v107, 0xbfb8aa3b, v7
	v_mul_f32_e32 v108, 0xbfb8aa3b, v8
	v_mul_f32_e32 v109, 0xbfb8aa3b, v9
	v_mul_f32_e32 v110, 0xbfb8aa3b, v10
	v_mul_f32_e32 v111, 0xbfb8aa3b, v11
	v_mul_f32_e32 v112, 0xbfb8aa3b, v12
	v_mul_f32_e32 v113, 0xbfb8aa3b, v13
	v_mul_f32_e32 v114, 0xbfb8aa3b, v14
	v_mul_f32_e32 v115, 0xbfb8aa3b, v15
	v_exp_f32_e32 v84, v84
	v_exp_f32_e32 v85, v85
	v_exp_f32_e32 v86, v86
	v_exp_f32_e32 v87, v87
	v_exp_f32_e32 v88, v88
	v_exp_f32_e32 v89, v89
	v_exp_f32_e32 v90, v90
	v_exp_f32_e32 v91, v91
	v_exp_f32_e32 v92, v92
	v_exp_f32_e32 v93, v93
	v_exp_f32_e32 v94, v94
	v_exp_f32_e32 v95, v95
	v_exp_f32_e32 v96, v96
	v_exp_f32_e32 v97, v97
	v_exp_f32_e32 v98, v98
	v_exp_f32_e32 v99, v99
	v_exp_f32_e32 v100, v100
	v_exp_f32_e32 v101, v101
	v_exp_f32_e32 v102, v102
	v_exp_f32_e32 v103, v103
	v_exp_f32_e32 v104, v104
	v_exp_f32_e32 v105, v105
	v_exp_f32_e32 v106, v106
	v_exp_f32_e32 v107, v107
	v_exp_f32_e32 v108, v108
	v_exp_f32_e32 v109, v109
	v_exp_f32_e32 v110, v110
	v_exp_f32_e32 v111, v111
	v_exp_f32_e32 v112, v112
	v_exp_f32_e32 v113, v113
	v_exp_f32_e32 v114, v114
	v_exp_f32_e32 v115, v115
	v_add_f32_e32 v84, 1.0, v84
	v_add_f32_e32 v85, 1.0, v85
	v_add_f32_e32 v86, 1.0, v86
	v_add_f32_e32 v87, 1.0, v87
	v_add_f32_e32 v88, 1.0, v88
	v_add_f32_e32 v89, 1.0, v89
	v_add_f32_e32 v90, 1.0, v90
	v_add_f32_e32 v91, 1.0, v91
	v_add_f32_e32 v92, 1.0, v92
	v_add_f32_e32 v93, 1.0, v93
	v_add_f32_e32 v94, 1.0, v94
	v_add_f32_e32 v95, 1.0, v95
	v_add_f32_e32 v96, 1.0, v96
	v_add_f32_e32 v97, 1.0, v97
	v_add_f32_e32 v98, 1.0, v98
	v_add_f32_e32 v99, 1.0, v99
	v_add_f32_e32 v100, 1.0, v100
	v_add_f32_e32 v101, 1.0, v101
	v_add_f32_e32 v102, 1.0, v102
	v_add_f32_e32 v103, 1.0, v103
	v_add_f32_e32 v104, 1.0, v104
	v_add_f32_e32 v105, 1.0, v105
	v_add_f32_e32 v106, 1.0, v106
	v_add_f32_e32 v107, 1.0, v107
	v_add_f32_e32 v108, 1.0, v108
	v_add_f32_e32 v109, 1.0, v109
	v_add_f32_e32 v110, 1.0, v110
	v_add_f32_e32 v111, 1.0, v111
	v_add_f32_e32 v112, 1.0, v112
	v_add_f32_e32 v113, 1.0, v113
	v_add_f32_e32 v114, 1.0, v114
	v_add_f32_e32 v115, 1.0, v115
	v_rcp_f32_e32 v84, v84
	v_rcp_f32_e32 v85, v85
	v_rcp_f32_e32 v86, v86
	v_rcp_f32_e32 v87, v87
	v_rcp_f32_e32 v88, v88
	v_rcp_f32_e32 v89, v89
	v_rcp_f32_e32 v90, v90
	v_rcp_f32_e32 v91, v91
	v_rcp_f32_e32 v92, v92
	v_rcp_f32_e32 v93, v93
	v_rcp_f32_e32 v94, v94
	v_rcp_f32_e32 v95, v95
	v_rcp_f32_e32 v96, v96
	v_rcp_f32_e32 v97, v97
	v_rcp_f32_e32 v98, v98
	v_rcp_f32_e32 v99, v99
	v_rcp_f32_e32 v100, v100
	v_rcp_f32_e32 v101, v101
	v_rcp_f32_e32 v102, v102
	v_rcp_f32_e32 v103, v103
	v_rcp_f32_e32 v104, v104
	v_rcp_f32_e32 v105, v105
	v_rcp_f32_e32 v106, v106
	v_rcp_f32_e32 v107, v107
	v_rcp_f32_e32 v108, v108
	v_rcp_f32_e32 v109, v109
	v_rcp_f32_e32 v110, v110
	v_rcp_f32_e32 v111, v111
	v_rcp_f32_e32 v112, v112
	v_rcp_f32_e32 v113, v113
	v_rcp_f32_e32 v114, v114
	v_rcp_f32_e32 v115, v115
	s_and_saveexec_b64 s[32:33], s[4:5]
	global_store_dword v36, v84, s[80:81]
	global_store_dword v36, v85, s[80:81] offset:96
	global_store_dword v36, v86, s[80:81] offset:192
	global_store_dword v36, v87, s[80:81] offset:288
	global_store_dword v36, v88, s[80:81] offset:768
	global_store_dword v36, v89, s[80:81] offset:864
	global_store_dword v36, v90, s[80:81] offset:960
	global_store_dword v36, v91, s[80:81] offset:1056
	global_store_dword v36, v92, s[80:81] offset:1536
	global_store_dword v36, v93, s[80:81] offset:1632
	global_store_dword v36, v94, s[80:81] offset:1728
	global_store_dword v36, v95, s[80:81] offset:1824
	global_store_dword v36, v96, s[80:81] offset:2304
	global_store_dword v36, v97, s[80:81] offset:2400
	global_store_dword v36, v98, s[80:81] offset:2496
	global_store_dword v36, v99, s[80:81] offset:2592
	global_store_dword v37, v100, s[80:81]
	global_store_dword v37, v101, s[80:81] offset:96
	global_store_dword v37, v102, s[80:81] offset:192
	global_store_dword v37, v103, s[80:81] offset:288
	global_store_dword v37, v104, s[80:81] offset:768
	global_store_dword v37, v105, s[80:81] offset:864
	global_store_dword v37, v106, s[80:81] offset:960
	global_store_dword v37, v107, s[80:81] offset:1056
	global_store_dword v37, v108, s[80:81] offset:1536
	global_store_dword v37, v109, s[80:81] offset:1632
	global_store_dword v37, v110, s[80:81] offset:1728
	global_store_dword v37, v111, s[80:81] offset:1824
	global_store_dword v37, v112, s[80:81] offset:2304
	global_store_dword v37, v113, s[80:81] offset:2400
	global_store_dword v37, v114, s[80:81] offset:2496
	global_store_dword v37, v115, s[80:81] offset:2592
	s_or_b64 exec, exec, s[32:33]
.Lp3a_done:
	s_mov_b32 s79, 0x800000
	s_branch .LBB0_1111
